# MoE: expert-count prefix read with one wave-wide load + scalar scan (was 64 serialized sc1 loads by one lane); GU row-offset table build issues its 26 loads before one wait
# speedup vs baseline: 1.0115x; 1.0064x over previous
; __device__ __forceinline__ int lane_id() { int l; asm volatile("v_mbcnt_lo_u32_b32 %0, -1, 0\n\tv_mbcnt_hi_u32_b32 %0, -1, %0" : "=v"(l)); return l; }
; __device__ __forceinline__ void moe_prefix(const Args& a, int l, unsigned char* ldsg, const int wid_s) {
;     int* ts = (int*)(ldsg + MISC_OFF);
;     __syncthreads();
;     if (wid_s == 0 && lane_id() == 0) {
;         const int* cnt = (const int*)(a.ws + WS_CTL) + l * 32; int acc_ = 0;
; #pragma unroll 1
;         for (int e = 0; e < 32; ++e) { ts[e] = acc_; ts[40 + e] = __hip_atomic_load(cnt + e, __ATOMIC_RELAXED, __HIP_MEMORY_SCOPE_AGENT); acc_ += (__hip_atomic_load(cnt + e, __ATOMIC_RELAXED, __HIP_MEMORY_SCOPE_AGENT) + 255) >> 8; }
;         ts[32] = acc_;
;     }
;     __syncthreads();
; }
.LBB0_671:
	v_readlane_b32 s4, v247, 55
	s_lshl_b64 s[0:1], s[76:77], 2
	v_readlane_b32 s6, v247, 57
	v_readlane_b32 s2, v249, 14
	v_readlane_b32 s7, v247, 58
	s_add_u32 s0, s6, s0
	v_readlane_b32 s3, v249, 15
	s_addc_u32 s1, s7, s1
	s_and_b64 vcc, exec, s[2:3]
	s_barrier
	v_readlane_b32 s5, v247, 56
	s_barrier
	s_cbranch_vccz .LBB0_677
	v_mbcnt_lo_u32_b32 v0, -1, 0
	v_mbcnt_hi_u32_b32 v0, -1, v0
	s_nop 0
	v_cmp_gt_u32_e32 vcc, 32, v0
	s_and_saveexec_b64 s[2:3], vcc
	s_cbranch_execz .LBB0_676
	v_lshlrev_b32_e32 v1, 2, v0
	global_load_dword v2, v1, s[0:1] sc1
	v_add_u32_e32 v1, 0x200a0, v1
	v_mov_b32_e32 v0, 0
	s_mov_b32 s4, 0
	s_mov_b32 s6, 0
	s_waitcnt vmcnt(0)
	ds_write_b32 v1, v2
	v_add_u32_e32 v2, 0xff, v2
	v_ashrrev_i32_e32 v2, 8, v2
	s_nop 1
.Lmoe_scan_1:
	s_mov_b32 m0, s6
	v_readlane_b32 s5, v2, s6
	v_writelane_b32 v0, s4, m0
	s_nop 1
	s_add_i32 s4, s4, s5
	s_add_i32 s6, s6, 1
	s_cmp_lt_u32 s6, 32
	s_cbranch_scc1 .Lmoe_scan_1
	v_add_u32_e32 v1, 0xffffff60, v1
	ds_write_b32 v1, v0
	v_mov_b32_e32 v1, 0x20080
	v_mov_b32_e32 v2, s4
	ds_write_b32 v1, v2

; __device__ __forceinline__ int lane_id() { int l; asm volatile("v_mbcnt_lo_u32_b32 %0, -1, 0\n\tv_mbcnt_hi_u32_b32 %0, -1, %0" : "=v"(l)); return l; }
; __device__ __forceinline__ void moe_prefix(const Args& a, int l, unsigned char* ldsg, const int wid_s) {
;     int* ts = (int*)(ldsg + MISC_OFF);
;     __syncthreads();
;     if (wid_s == 0 && lane_id() == 0) {
;         const int* cnt = (const int*)(a.ws + WS_CTL) + l * 32; int acc_ = 0;
; #pragma unroll 1
;         for (int e = 0; e < 32; ++e) { ts[e] = acc_; ts[40 + e] = __hip_atomic_load(cnt + e, __ATOMIC_RELAXED, __HIP_MEMORY_SCOPE_AGENT); acc_ += (__hip_atomic_load(cnt + e, __ATOMIC_RELAXED, __HIP_MEMORY_SCOPE_AGENT) + 255) >> 8; }
;         ts[32] = acc_;
;     }
;     __syncthreads();
; }
.LBB0_694:
	v_readlane_b32 s2, v249, 14
	v_readlane_b32 s3, v249, 15
	s_and_b64 vcc, exec, s[2:3]
	s_barrier
	s_barrier
	s_cbranch_vccz .LBB0_700
	v_mbcnt_lo_u32_b32 v0, -1, 0
	v_mbcnt_hi_u32_b32 v0, -1, v0
	s_nop 0
	v_cmp_gt_u32_e32 vcc, 32, v0
	s_and_saveexec_b64 s[2:3], vcc
	s_cbranch_execz .LBB0_699
	v_lshlrev_b32_e32 v1, 2, v0
	global_load_dword v2, v1, s[0:1] sc1
	v_add_u32_e32 v1, 0x200a0, v1
	v_mov_b32_e32 v0, 0
	s_mov_b32 s4, 0
	s_mov_b32 s6, 0
	s_waitcnt vmcnt(0)
	ds_write_b32 v1, v2
	v_add_u32_e32 v2, 0xff, v2
	v_ashrrev_i32_e32 v2, 8, v2
	s_nop 1

; #define LAS __attribute__((address_space(3)))
; __device__ __forceinline__ int mk_tid(int wid_s) { return wid_s * 64 + lane_id(); }
; __global__ void __launch_bounds__(NTHREADS, 2) mk_fwd(Args a) {
;     ...
;             {
;                 const int tid = mk_tid(wid_s); const int* RO = (const int*)(ws + WS_ROWOFF); LAS int* tab = (LAS int*)(ldsl + GTAB_OFF);
;                 pg8::Unit uu;
;                 for (int i = 0; i < 27 && S.next(i, uu); ++i) if (tid < 256) tab[i * 256 + tid] = RO[uu.pm * 256 + tid];
;                 __syncthreads();
.LBB0_703:
	s_and_b64 vcc, exec, s[0:1]
	s_cbranch_vccz .LBB0_863
	v_readlane_b32 s2, v249, 8
	s_nop 1
	v_add_u32_e32 v1, s2, v0
	v_readlane_b32 s2, v250, 3
	s_nop 1
	v_lshl_add_u32 v0, v1, 2, s2
	s_movk_i32 s2, 0xff
	v_cmp_lt_i32_e64 s[6:7], s2, v1
	s_movk_i32 s2, 0x100
	v_cmp_gt_i32_e64 s[4:5], s2, v1
	s_and_saveexec_b64 s[2:3], s[4:5]
	v_readlane_b32 s10, v248, 16
	v_readlane_b32 s11, v248, 17
	s_cbranch_execz .LBB0_706
	v_readlane_b32 s8, v244, 2
	s_nop 1
	v_lshl_add_u32 v2, s8, 8, v1
	v_ashrrev_i32_e32 v3, 31, v2
	v_lshl_add_u64 v[2:3], v[2:3], 2, s[10:11]
	global_load_dword v10, v[2:3], off

; __global__ void __launch_bounds__(NTHREADS, 2) mk_fwd(Args a) {
;     ...
;                 for (int i = 0; i < 27 && S.next(i, uu); ++i) if (tid < 256) tab[i * 256 + tid] = RO[uu.pm * 256 + tid];
.LBB0_709:
	s_andn2_b64 vcc, exec, s[2:3]
	s_cbranch_vccnz .Ltab_flush
	s_and_saveexec_b64 s[2:3], s[4:5]
	v_readlane_b32 s10, v248, 16
	v_readlane_b32 s11, v248, 17
	s_cbranch_execz .LBB0_712
	v_readlane_b32 s8, v244, 2
	s_nop 1
	v_lshl_add_u32 v2, s8, 8, v1
	v_ashrrev_i32_e32 v3, 31, v2
	v_lshl_add_u64 v[2:3], v[2:3], 2, s[10:11]
	global_load_dword v11, v[2:3], off

; __global__ void __launch_bounds__(NTHREADS, 2) mk_fwd(Args a) {
;     ...
;                 for (int i = 0; i < 27 && S.next(i, uu); ++i) if (tid < 256) tab[i * 256 + tid] = RO[uu.pm * 256 + tid];
.LBB0_715:
	s_andn2_b64 vcc, exec, s[2:3]
	s_cbranch_vccnz .Ltab_flush
	s_and_saveexec_b64 s[2:3], s[4:5]
	v_readlane_b32 s10, v248, 16
	v_readlane_b32 s11, v248, 17
	s_cbranch_execz .LBB0_718
	v_readlane_b32 s8, v244, 2
	s_nop 1
	v_lshl_add_u32 v2, s8, 8, v1
	v_ashrrev_i32_e32 v3, 31, v2
	v_lshl_add_u64 v[2:3], v[2:3], 2, s[10:11]
	global_load_dword v12, v[2:3], off

; __global__ void __launch_bounds__(NTHREADS, 2) mk_fwd(Args a) {
;     ...
;                 for (int i = 0; i < 27 && S.next(i, uu); ++i) if (tid < 256) tab[i * 256 + tid] = RO[uu.pm * 256 + tid];
.LBB0_721:
	s_andn2_b64 vcc, exec, s[2:3]
	s_cbranch_vccnz .Ltab_flush
	s_and_saveexec_b64 s[2:3], s[4:5]
	v_readlane_b32 s10, v248, 16
	v_readlane_b32 s11, v248, 17
	s_cbranch_execz .LBB0_724
	v_readlane_b32 s8, v244, 2
	s_nop 1
	v_lshl_add_u32 v2, s8, 8, v1
	v_ashrrev_i32_e32 v3, 31, v2
	v_lshl_add_u64 v[2:3], v[2:3], 2, s[10:11]
	global_load_dword v13, v[2:3], off

; __global__ void __launch_bounds__(NTHREADS, 2) mk_fwd(Args a) {
;     ...
;                 for (int i = 0; i < 27 && S.next(i, uu); ++i) if (tid < 256) tab[i * 256 + tid] = RO[uu.pm * 256 + tid];
.LBB0_727:
	s_andn2_b64 vcc, exec, s[2:3]
	s_cbranch_vccnz .Ltab_flush
	s_and_saveexec_b64 s[2:3], s[4:5]
	v_readlane_b32 s10, v248, 16
	v_readlane_b32 s11, v248, 17
	s_cbranch_execz .LBB0_730
	v_readlane_b32 s8, v244, 2
	s_nop 1
	v_lshl_add_u32 v2, s8, 8, v1
	v_ashrrev_i32_e32 v3, 31, v2
	v_lshl_add_u64 v[2:3], v[2:3], 2, s[10:11]
	global_load_dword v14, v[2:3], off

; __global__ void __launch_bounds__(NTHREADS, 2) mk_fwd(Args a) {
;     ...
;                 for (int i = 0; i < 27 && S.next(i, uu); ++i) if (tid < 256) tab[i * 256 + tid] = RO[uu.pm * 256 + tid];
.LBB0_733:
	s_andn2_b64 vcc, exec, s[2:3]
	s_cbranch_vccnz .Ltab_flush
	s_and_saveexec_b64 s[2:3], s[4:5]
	v_readlane_b32 s10, v248, 16
	v_readlane_b32 s11, v248, 17
	s_cbranch_execz .LBB0_736
	v_readlane_b32 s8, v244, 2
	s_nop 1
	v_lshl_add_u32 v2, s8, 8, v1
	v_ashrrev_i32_e32 v3, 31, v2
	v_lshl_add_u64 v[2:3], v[2:3], 2, s[10:11]
	global_load_dword v15, v[2:3], off

; __global__ void __launch_bounds__(NTHREADS, 2) mk_fwd(Args a) {
;     ...
;                 for (int i = 0; i < 27 && S.next(i, uu); ++i) if (tid < 256) tab[i * 256 + tid] = RO[uu.pm * 256 + tid];
.LBB0_739:
	s_andn2_b64 vcc, exec, s[2:3]
	s_cbranch_vccnz .Ltab_flush
	s_and_saveexec_b64 s[2:3], s[4:5]
	v_readlane_b32 s10, v248, 16
	v_readlane_b32 s11, v248, 17
	s_cbranch_execz .LBB0_742
	v_readlane_b32 s8, v244, 2
	s_nop 1
	v_lshl_add_u32 v2, s8, 8, v1
	v_ashrrev_i32_e32 v3, 31, v2
	v_lshl_add_u64 v[2:3], v[2:3], 2, s[10:11]
	global_load_dword v16, v[2:3], off

; __global__ void __launch_bounds__(NTHREADS, 2) mk_fwd(Args a) {
;     ...
;                 for (int i = 0; i < 27 && S.next(i, uu); ++i) if (tid < 256) tab[i * 256 + tid] = RO[uu.pm * 256 + tid];
.LBB0_745:
	s_andn2_b64 vcc, exec, s[2:3]
	s_cbranch_vccnz .Ltab_flush
	s_and_saveexec_b64 s[2:3], s[4:5]
	v_readlane_b32 s10, v248, 16
	v_readlane_b32 s11, v248, 17
	s_cbranch_execz .LBB0_748
	v_readlane_b32 s8, v244, 2
	s_nop 1
	v_lshl_add_u32 v2, s8, 8, v1
	v_ashrrev_i32_e32 v3, 31, v2
	v_lshl_add_u64 v[2:3], v[2:3], 2, s[10:11]
	global_load_dword v17, v[2:3], off

; __global__ void __launch_bounds__(NTHREADS, 2) mk_fwd(Args a) {
;     ...
;                 for (int i = 0; i < 27 && S.next(i, uu); ++i) if (tid < 256) tab[i * 256 + tid] = RO[uu.pm * 256 + tid];
.LBB0_751:
	s_andn2_b64 vcc, exec, s[2:3]
	s_cbranch_vccnz .Ltab_flush
	s_and_saveexec_b64 s[2:3], s[4:5]
	v_readlane_b32 s10, v248, 16
	v_readlane_b32 s11, v248, 17
	s_cbranch_execz .LBB0_754
	v_readlane_b32 s8, v244, 2
	s_nop 1
	v_lshl_add_u32 v2, s8, 8, v1
	v_ashrrev_i32_e32 v3, 31, v2
	v_lshl_add_u64 v[2:3], v[2:3], 2, s[10:11]
	global_load_dword v18, v[2:3], off

; __global__ void __launch_bounds__(NTHREADS, 2) mk_fwd(Args a) {
;     ...
;                 for (int i = 0; i < 27 && S.next(i, uu); ++i) if (tid < 256) tab[i * 256 + tid] = RO[uu.pm * 256 + tid];
.LBB0_757:
	s_andn2_b64 vcc, exec, s[2:3]
	s_cbranch_vccnz .Ltab_flush
	s_and_saveexec_b64 s[2:3], s[4:5]
	v_readlane_b32 s10, v248, 16
	v_readlane_b32 s11, v248, 17
	s_cbranch_execz .LBB0_760
	v_readlane_b32 s8, v244, 2
	s_nop 1
	v_lshl_add_u32 v2, s8, 8, v1
	v_ashrrev_i32_e32 v3, 31, v2
	v_lshl_add_u64 v[2:3], v[2:3], 2, s[10:11]
	global_load_dword v19, v[2:3], off

; __global__ void __launch_bounds__(NTHREADS, 2) mk_fwd(Args a) {
;     ...
;                 for (int i = 0; i < 27 && S.next(i, uu); ++i) if (tid < 256) tab[i * 256 + tid] = RO[uu.pm * 256 + tid];
.LBB0_763:
	s_andn2_b64 vcc, exec, s[2:3]
	s_cbranch_vccnz .Ltab_flush
	s_and_saveexec_b64 s[2:3], s[4:5]
	v_readlane_b32 s10, v248, 16
	v_readlane_b32 s11, v248, 17
	s_cbranch_execz .LBB0_766
	v_readlane_b32 s8, v244, 2
	s_nop 1
	v_lshl_add_u32 v2, s8, 8, v1
	v_ashrrev_i32_e32 v3, 31, v2
	v_lshl_add_u64 v[2:3], v[2:3], 2, s[10:11]
	global_load_dword v20, v[2:3], off

; __global__ void __launch_bounds__(NTHREADS, 2) mk_fwd(Args a) {
;     ...
;                 for (int i = 0; i < 27 && S.next(i, uu); ++i) if (tid < 256) tab[i * 256 + tid] = RO[uu.pm * 256 + tid];
.LBB0_769:
	s_andn2_b64 vcc, exec, s[2:3]
	s_cbranch_vccnz .Ltab_flush
	s_and_saveexec_b64 s[2:3], s[4:5]
	v_readlane_b32 s10, v248, 16
	v_readlane_b32 s11, v248, 17
	s_cbranch_execz .LBB0_772
	v_readlane_b32 s8, v244, 2
	s_nop 1
	v_lshl_add_u32 v2, s8, 8, v1
	v_ashrrev_i32_e32 v3, 31, v2
	v_lshl_add_u64 v[2:3], v[2:3], 2, s[10:11]
	global_load_dword v21, v[2:3], off

; __global__ void __launch_bounds__(NTHREADS, 2) mk_fwd(Args a) {
;     ...
;                 for (int i = 0; i < 27 && S.next(i, uu); ++i) if (tid < 256) tab[i * 256 + tid] = RO[uu.pm * 256 + tid];
.LBB0_775:
	s_andn2_b64 vcc, exec, s[2:3]
	s_cbranch_vccnz .Ltab_flush
	s_and_saveexec_b64 s[2:3], s[4:5]
	v_readlane_b32 s10, v248, 16
	v_readlane_b32 s11, v248, 17
	s_cbranch_execz .LBB0_778
	v_readlane_b32 s8, v244, 2
	s_nop 1
	v_lshl_add_u32 v2, s8, 8, v1
	v_ashrrev_i32_e32 v3, 31, v2
	v_lshl_add_u64 v[2:3], v[2:3], 2, s[10:11]
	global_load_dword v22, v[2:3], off

; __global__ void __launch_bounds__(NTHREADS, 2) mk_fwd(Args a) {
;     ...
;                 for (int i = 0; i < 27 && S.next(i, uu); ++i) if (tid < 256) tab[i * 256 + tid] = RO[uu.pm * 256 + tid];
.LBB0_781:
	s_andn2_b64 vcc, exec, s[2:3]
	s_cbranch_vccnz .Ltab_flush
	s_and_saveexec_b64 s[2:3], s[4:5]
	v_readlane_b32 s10, v248, 16
	v_readlane_b32 s11, v248, 17
	s_cbranch_execz .LBB0_784
	v_readlane_b32 s8, v244, 2
	s_nop 1
	v_lshl_add_u32 v2, s8, 8, v1
	v_ashrrev_i32_e32 v3, 31, v2
	v_lshl_add_u64 v[2:3], v[2:3], 2, s[10:11]
	global_load_dword v23, v[2:3], off

; __global__ void __launch_bounds__(NTHREADS, 2) mk_fwd(Args a) {
;     ...
;                 for (int i = 0; i < 27 && S.next(i, uu); ++i) if (tid < 256) tab[i * 256 + tid] = RO[uu.pm * 256 + tid];
.LBB0_787:
	s_andn2_b64 vcc, exec, s[2:3]
	s_cbranch_vccnz .Ltab_flush
	s_and_saveexec_b64 s[2:3], s[4:5]
	v_readlane_b32 s10, v248, 16
	v_readlane_b32 s11, v248, 17
	s_cbranch_execz .LBB0_790
	v_readlane_b32 s8, v244, 2
	s_nop 1
	v_lshl_add_u32 v2, s8, 8, v1
	v_ashrrev_i32_e32 v3, 31, v2
	v_lshl_add_u64 v[2:3], v[2:3], 2, s[10:11]
	global_load_dword v24, v[2:3], off

; __global__ void __launch_bounds__(NTHREADS, 2) mk_fwd(Args a) {
;     ...
;                 for (int i = 0; i < 27 && S.next(i, uu); ++i) if (tid < 256) tab[i * 256 + tid] = RO[uu.pm * 256 + tid];
.LBB0_793:
	s_andn2_b64 vcc, exec, s[2:3]
	s_cbranch_vccnz .Ltab_flush
	s_and_saveexec_b64 s[2:3], s[4:5]
	v_readlane_b32 s10, v248, 16
	v_readlane_b32 s11, v248, 17
	s_cbranch_execz .LBB0_796
	v_readlane_b32 s8, v244, 2
	s_nop 1
	v_lshl_add_u32 v2, s8, 8, v1
	v_ashrrev_i32_e32 v3, 31, v2
	v_lshl_add_u64 v[2:3], v[2:3], 2, s[10:11]
	global_load_dword v25, v[2:3], off

; __global__ void __launch_bounds__(NTHREADS, 2) mk_fwd(Args a) {
;     ...
;                 for (int i = 0; i < 27 && S.next(i, uu); ++i) if (tid < 256) tab[i * 256 + tid] = RO[uu.pm * 256 + tid];
.LBB0_799:
	s_andn2_b64 vcc, exec, s[2:3]
	s_cbranch_vccnz .Ltab_flush
	s_and_saveexec_b64 s[2:3], s[4:5]
	v_readlane_b32 s10, v248, 16
	v_readlane_b32 s11, v248, 17
	s_cbranch_execz .LBB0_802
	v_readlane_b32 s8, v244, 2
	s_nop 1
	v_lshl_add_u32 v2, s8, 8, v1
	v_ashrrev_i32_e32 v3, 31, v2
	v_lshl_add_u64 v[2:3], v[2:3], 2, s[10:11]
	global_load_dword v26, v[2:3], off

; __global__ void __launch_bounds__(NTHREADS, 2) mk_fwd(Args a) {
;     ...
;                 for (int i = 0; i < 27 && S.next(i, uu); ++i) if (tid < 256) tab[i * 256 + tid] = RO[uu.pm * 256 + tid];
.LBB0_805:
	s_andn2_b64 vcc, exec, s[2:3]
	s_cbranch_vccnz .Ltab_flush
	s_and_saveexec_b64 s[2:3], s[4:5]
	v_readlane_b32 s10, v248, 16
	v_readlane_b32 s11, v248, 17
	s_cbranch_execz .LBB0_808
	v_readlane_b32 s8, v244, 2
	s_nop 1
	v_lshl_add_u32 v2, s8, 8, v1
	v_ashrrev_i32_e32 v3, 31, v2
	v_lshl_add_u64 v[2:3], v[2:3], 2, s[10:11]
	global_load_dword v27, v[2:3], off

; __global__ void __launch_bounds__(NTHREADS, 2) mk_fwd(Args a) {
;     ...
;                 for (int i = 0; i < 27 && S.next(i, uu); ++i) if (tid < 256) tab[i * 256 + tid] = RO[uu.pm * 256 + tid];
.LBB0_811:
	s_andn2_b64 vcc, exec, s[2:3]
	s_cbranch_vccnz .Ltab_flush
	s_and_saveexec_b64 s[2:3], s[4:5]
	s_cbranch_execz .LBB0_814
	v_readlane_b32 s8, v244, 2
	s_nop 1
	v_lshl_add_u32 v2, s8, 8, v1
	v_readlane_b32 s8, v248, 16
	v_ashrrev_i32_e32 v3, 31, v2
	v_readlane_b32 s9, v248, 17
	s_nop 1
	v_lshl_add_u64 v[2:3], v[2:3], 2, s[8:9]
	global_load_dword v28, v[2:3], off

; #define LAS __attribute__((address_space(3)))
; __device__ __forceinline__ int mk_tid(int wid_s) { return wid_s * 64 + lane_id(); }
; __global__ void __launch_bounds__(NTHREADS, 2) mk_fwd(Args a) {
;     ...
;                 const int tid = mk_tid(wid_s); const int* RO = (const int*)(ws + WS_ROWOFF); LAS int* tab = (LAS int*)(ldsl + GTAB_OFF);
;                 pg8::Unit uu;
;                 for (int i = 0; i < 27 && S.next(i, uu); ++i) if (tid < 256) tab[i * 256 + tid] = RO[uu.pm * 256 + tid];
;                 __syncthreads();
.LBB0_817:
	s_andn2_b64 vcc, exec, s[2:3]
	s_cbranch_vccnz .Ltab_flush
	s_and_saveexec_b64 s[2:3], s[4:5]
	s_cbranch_execz .LBB0_820
	v_readlane_b32 s8, v244, 2
	s_nop 1
	v_lshl_add_u32 v2, s8, 8, v1
	v_readlane_b32 s8, v248, 16
	v_ashrrev_i32_e32 v3, 31, v2
	v_readlane_b32 s9, v248, 17
	s_nop 1
	v_lshl_add_u64 v[2:3], v[2:3], 2, s[8:9]
	global_load_dword v29, v[2:3], off

; #define LAS __attribute__((address_space(3)))
; __device__ __forceinline__ int mk_tid(int wid_s) { return wid_s * 64 + lane_id(); }
; __global__ void __launch_bounds__(NTHREADS, 2) mk_fwd(Args a) {
;     ...
;                 const int tid = mk_tid(wid_s); const int* RO = (const int*)(ws + WS_ROWOFF); LAS int* tab = (LAS int*)(ldsl + GTAB_OFF);
;                 pg8::Unit uu;
;                 for (int i = 0; i < 27 && S.next(i, uu); ++i) if (tid < 256) tab[i * 256 + tid] = RO[uu.pm * 256 + tid];
;                 __syncthreads();
.LBB0_823:
	s_andn2_b64 vcc, exec, s[2:3]
	s_cbranch_vccnz .Ltab_flush
	s_and_saveexec_b64 s[2:3], s[4:5]
	s_cbranch_execz .LBB0_826
	v_readlane_b32 s8, v244, 2
	s_nop 1
	v_lshl_add_u32 v2, s8, 8, v1
	v_readlane_b32 s8, v248, 16
	v_ashrrev_i32_e32 v3, 31, v2
	v_readlane_b32 s9, v248, 17
	s_nop 1
	v_lshl_add_u64 v[2:3], v[2:3], 2, s[8:9]
	global_load_dword v30, v[2:3], off

; #define LAS __attribute__((address_space(3)))
; __device__ __forceinline__ int mk_tid(int wid_s) { return wid_s * 64 + lane_id(); }
; __global__ void __launch_bounds__(NTHREADS, 2) mk_fwd(Args a) {
;     ...
;                 const int tid = mk_tid(wid_s); const int* RO = (const int*)(ws + WS_ROWOFF); LAS int* tab = (LAS int*)(ldsl + GTAB_OFF);
;                 pg8::Unit uu;
;                 for (int i = 0; i < 27 && S.next(i, uu); ++i) if (tid < 256) tab[i * 256 + tid] = RO[uu.pm * 256 + tid];
;                 __syncthreads();
.LBB0_829:
	s_andn2_b64 vcc, exec, s[2:3]
	s_cbranch_vccnz .Ltab_flush
	s_and_saveexec_b64 s[2:3], s[4:5]
	s_cbranch_execz .LBB0_832
	v_readlane_b32 s8, v244, 2
	s_nop 1
	v_lshl_add_u32 v2, s8, 8, v1
	v_readlane_b32 s8, v248, 16
	v_ashrrev_i32_e32 v3, 31, v2
	v_readlane_b32 s9, v248, 17
	s_nop 1
	v_lshl_add_u64 v[2:3], v[2:3], 2, s[8:9]
	global_load_dword v31, v[2:3], off

; #define LAS __attribute__((address_space(3)))
; __device__ __forceinline__ int mk_tid(int wid_s) { return wid_s * 64 + lane_id(); }
; __global__ void __launch_bounds__(NTHREADS, 2) mk_fwd(Args a) {
;     ...
;                 const int tid = mk_tid(wid_s); const int* RO = (const int*)(ws + WS_ROWOFF); LAS int* tab = (LAS int*)(ldsl + GTAB_OFF);
;                 pg8::Unit uu;
;                 for (int i = 0; i < 27 && S.next(i, uu); ++i) if (tid < 256) tab[i * 256 + tid] = RO[uu.pm * 256 + tid];
;                 __syncthreads();
.LBB0_835:
	s_andn2_b64 vcc, exec, s[2:3]
	s_cbranch_vccnz .Ltab_flush
	s_and_saveexec_b64 s[2:3], s[4:5]
	s_cbranch_execz .LBB0_838
	v_readlane_b32 s8, v244, 2
	s_nop 1
	v_lshl_add_u32 v2, s8, 8, v1
	v_readlane_b32 s8, v248, 16
	v_ashrrev_i32_e32 v3, 31, v2
	v_readlane_b32 s9, v248, 17
	s_nop 1
	v_lshl_add_u64 v[2:3], v[2:3], 2, s[8:9]
	global_load_dword v32, v[2:3], off

; #define LAS __attribute__((address_space(3)))
; __device__ __forceinline__ int mk_tid(int wid_s) { return wid_s * 64 + lane_id(); }
; __global__ void __launch_bounds__(NTHREADS, 2) mk_fwd(Args a) {
;     ...
;                 const int tid = mk_tid(wid_s); const int* RO = (const int*)(ws + WS_ROWOFF); LAS int* tab = (LAS int*)(ldsl + GTAB_OFF);
;                 pg8::Unit uu;
;                 for (int i = 0; i < 27 && S.next(i, uu); ++i) if (tid < 256) tab[i * 256 + tid] = RO[uu.pm * 256 + tid];
;                 __syncthreads();
.LBB0_841:
	s_andn2_b64 vcc, exec, s[2:3]
	s_cbranch_vccnz .Ltab_flush
	s_and_saveexec_b64 s[2:3], s[4:5]
	s_cbranch_execz .LBB0_844
	v_readlane_b32 s8, v244, 2
	s_nop 1
	v_lshl_add_u32 v2, s8, 8, v1
	v_readlane_b32 s8, v248, 16
	v_ashrrev_i32_e32 v3, 31, v2
	v_readlane_b32 s9, v248, 17
	s_nop 1
	v_lshl_add_u64 v[2:3], v[2:3], 2, s[8:9]
	global_load_dword v33, v[2:3], off

; #define LAS __attribute__((address_space(3)))
; __device__ __forceinline__ int mk_tid(int wid_s) { return wid_s * 64 + lane_id(); }
; __global__ void __launch_bounds__(NTHREADS, 2) mk_fwd(Args a) {
;     ...
;                 const int tid = mk_tid(wid_s); const int* RO = (const int*)(ws + WS_ROWOFF); LAS int* tab = (LAS int*)(ldsl + GTAB_OFF);
;                 pg8::Unit uu;
;                 for (int i = 0; i < 27 && S.next(i, uu); ++i) if (tid < 256) tab[i * 256 + tid] = RO[uu.pm * 256 + tid];
;                 __syncthreads();
.LBB0_847:
	s_andn2_b64 vcc, exec, s[2:3]
	s_cbranch_vccnz .Ltab_flush
	s_and_saveexec_b64 s[2:3], s[4:5]
	s_cbranch_execz .LBB0_850
	v_readlane_b32 s8, v244, 2
	s_nop 1
	v_lshl_add_u32 v2, s8, 8, v1
	v_readlane_b32 s8, v248, 16
	v_ashrrev_i32_e32 v3, 31, v2
	v_readlane_b32 s9, v248, 17
	s_nop 1
	v_lshl_add_u64 v[2:3], v[2:3], 2, s[8:9]
	global_load_dword v34, v[2:3], off

; #define LAS __attribute__((address_space(3)))
; __device__ __forceinline__ int mk_tid(int wid_s) { return wid_s * 64 + lane_id(); }
; __global__ void __launch_bounds__(NTHREADS, 2) mk_fwd(Args a) {
;     ...
;                 const int tid = mk_tid(wid_s); const int* RO = (const int*)(ws + WS_ROWOFF); LAS int* tab = (LAS int*)(ldsl + GTAB_OFF);
;                 pg8::Unit uu;
;                 for (int i = 0; i < 27 && S.next(i, uu); ++i) if (tid < 256) tab[i * 256 + tid] = RO[uu.pm * 256 + tid];
;                 __syncthreads();
.LBB0_853:
	s_andn2_b64 vcc, exec, s[2:3]
	s_cbranch_vccnz .Ltab_flush
	s_and_saveexec_b64 s[2:3], s[4:5]
	s_cbranch_execz .LBB0_856
	v_readlane_b32 s4, v244, 2
	s_nop 1
	v_lshl_add_u32 v2, s4, 8, v1
	v_readlane_b32 s4, v248, 16
	v_ashrrev_i32_e32 v3, 31, v2
	v_readlane_b32 s5, v248, 17
	s_nop 1
	v_lshl_add_u64 v[2:3], v[2:3], 2, s[4:5]
	global_load_dword v35, v[2:3], off

; #define LAS __attribute__((address_space(3)))
; __device__ __forceinline__ int mk_tid(int wid_s) { return wid_s * 64 + lane_id(); }
; __global__ void __launch_bounds__(NTHREADS, 2) mk_fwd(Args a) {
;     ...
;                 const int tid = mk_tid(wid_s); const int* RO = (const int*)(ws + WS_ROWOFF); LAS int* tab = (LAS int*)(ldsl + GTAB_OFF);
;                 pg8::Unit uu;
;                 for (int i = 0; i < 27 && S.next(i, uu); ++i) if (tid < 256) tab[i * 256 + tid] = RO[uu.pm * 256 + tid];
;                 __syncthreads();
.Ltab_flush:
	v_readlane_b32 s8, v249, 8
	s_nop 3
	s_cmp_lt_u32 s8, 0x100
	s_cbranch_scc0 .LBB0_863
	s_waitcnt vmcnt(0)
	ds_write_b32 v0, v10
	ds_write_b32 v0, v11 offset:1024
	ds_write_b32 v0, v12 offset:2048
	ds_write_b32 v0, v13 offset:3072
	ds_write_b32 v0, v14 offset:4096
	ds_write_b32 v0, v15 offset:5120
	ds_write_b32 v0, v16 offset:6144
	ds_write_b32 v0, v17 offset:7168
	ds_write_b32 v0, v18 offset:8192
	ds_write_b32 v0, v19 offset:9216
	ds_write_b32 v0, v20 offset:10240
	ds_write_b32 v0, v21 offset:11264
	ds_write_b32 v0, v22 offset:12288
	ds_write_b32 v0, v23 offset:13312
	ds_write_b32 v0, v24 offset:14336
	ds_write_b32 v0, v25 offset:15360
	ds_write_b32 v0, v26 offset:16384
	ds_write_b32 v0, v27 offset:17408
	ds_write_b32 v0, v28 offset:18432
	ds_write_b32 v0, v29 offset:19456
	ds_write_b32 v0, v30 offset:20480
	ds_write_b32 v0, v31 offset:21504
	ds_write_b32 v0, v32 offset:22528
	ds_write_b32 v0, v33 offset:23552
	ds_write_b32 v0, v34 offset:24576
	ds_write_b32 v0, v35 offset:25600
